# attention softmax/PV as 4-stage pipeline over k-slices with V fragments read 3 MFMAs ahead (on top of QK prefetch + PEER U pipelining)
# baseline (speedup 1.0000x reference)
; #define SBAR() __builtin_amdgcn_sched_barrier(0)
; __device__ __forceinline__ void partialSM(f32x16& p0, f32x16& p1, float& m_reg, float& mn, float& alpha, int rem, int hi) {
;     ...
;   else { mn = fmaxf(m_reg, pmax); alpha = __builtin_amdgcn_exp2f((m_reg - mn) * C); m_reg = mn; }
;   float mnC = -mn * C;
; #pragma unroll
;   for (int r = 0; r < 16; ++r) p0[r] = fmaf(p0[r], C, mnC);
; #pragma unroll
;   for (int r = 0; r < 16; ++r) p1[r] = fmaf(p1[r], C, mnC);
; #pragma unroll
;   for (int r = 0; r < 16; ++r) p0[r] = __builtin_amdgcn_exp2f(p0[r]);
; }
; __device__ __forceinline__ void finishSM(f32x16& p0, f32x16& p1, float alpha, float& l_reg, bf16x8& pa0, bf16x8& pa1, bf16x8& pa2, bf16x8& pa3) {
; #pragma unroll
;   for (int r = 0; r < 16; ++r) p1[r] = __builtin_amdgcn_exp2f(p1[r]);
;   float ps = 0;
; #pragma unroll
;   for (int r = 0; r < 16; ++r) ps += p0[r];
; #pragma unroll
;   for (int r = 0; r < 16; ++r) ps += p1[r];
;   { auto rr = __builtin_amdgcn_permlane32_swap(__float_as_uint(ps), __float_as_uint(ps), false, false);
;     ps = __uint_as_float(rr[0]) + __uint_as_float(rr[1]); }
;   l_reg = l_reg * alpha + ps;
;     ...
;   PK4(p0, 0, pa0); PK4(p0, 8, pa1); PK4(p1, 0, pa2); PK4(p1, 8, pa3);
;     ...
; }
; template <int D0> __device__ __forceinline__ void pv_one8(f32x16& od, int vb, bf16x8 pa0, bf16x8 pa1, bf16x8 pa2, bf16x8 pa3) {
;   constexpr int HB = (D0 >> 2) * 16384, DD = D0 & 3;
;   const s16x4 l0 = tr_read<HB + v_rd_off(DD, 0, 0)>(vb), h0 = tr_read<HB + v_rd_off(DD, 0, 1)>(vb), l1 = tr_read<HB + v_rd_off(DD, 1, 0)>(vb), h1 = tr_read<HB + v_rd_off(DD, 1, 1)>(vb);
;   const s16x4 l2 = tr_read<HB + v_rd_off(DD, 2, 0)>(vb), h2 = tr_read<HB + v_rd_off(DD, 2, 1)>(vb), l3 = tr_read<HB + v_rd_off(DD, 3, 0)>(vb), h3 = tr_read<HB + v_rd_off(DD, 3, 1)>(vb);
;   asm volatile("s_waitcnt lgkmcnt(0)" ::: "memory"); SBAR();
;     ...
;   od = __builtin_amdgcn_mfma_f32_32x32x16_bf16(pa0, PK(l0, h0), od, 0, 0, 0);
;   od = __builtin_amdgcn_mfma_f32_32x32x16_bf16(pa1, PK(l1, h1), od, 0, 0, 0);
;   od = __builtin_amdgcn_mfma_f32_32x32x16_bf16(pa2, PK(l2, h2), od, 0, 0, 0);
;   od = __builtin_amdgcn_mfma_f32_32x32x16_bf16(pa3, PK(l3, h3), od, 0, 0, 0);
.LBB0_937:
	v_cndmask_b32_e64 v246, v248, v246, s[4:5]
	v_mul_f32_e32 v194, 0xbe0293ee, v246
	v_fmamk_f32 v146, v146, 0x3e0293ee, v194
	v_fmamk_f32 v147, v147, 0x3e0293ee, v194
	v_fmamk_f32 v148, v148, 0x3e0293ee, v194
	v_fmamk_f32 v149, v149, 0x3e0293ee, v194
	v_fmamk_f32 v150, v150, 0x3e0293ee, v194
	v_fmamk_f32 v151, v151, 0x3e0293ee, v194
	v_fmamk_f32 v152, v152, 0x3e0293ee, v194
	v_fmamk_f32 v153, v153, 0x3e0293ee, v194
	v_fmamk_f32 v206, v154, 0x3e0293ee, v194
	v_fmamk_f32 v207, v155, 0x3e0293ee, v194
	v_fmamk_f32 v208, v156, 0x3e0293ee, v194
	v_fmamk_f32 v209, v157, 0x3e0293ee, v194
	v_fmamk_f32 v249, v158, 0x3e0293ee, v194
	v_fmamk_f32 v250, v159, 0x3e0293ee, v194
	v_fmamk_f32 v251, v160, 0x3e0293ee, v194
	v_fmamk_f32 v248, v161, 0x3e0293ee, v194
	v_exp_f32_e32 v146, v146
	v_exp_f32_e32 v147, v147
	v_exp_f32_e32 v148, v148
	v_exp_f32_e32 v149, v149
	v_exp_f32_e32 v150, v150
	v_exp_f32_e32 v151, v151
	v_exp_f32_e32 v152, v152
	v_exp_f32_e32 v153, v153
	s_add_i32 s29, s29, 0x8000
	v_add_u32_e32 v195, s29, v235
	v_add_f32_e32 v205, v146, v147
	v_add_f32_e32 v204, v148, v149
	v_add_f32_e32 v205, v150, v205
	v_add_f32_e32 v204, v151, v204
	v_add_f32_e32 v205, v152, v205
	v_add_f32_e32 v204, v153, v204
	v_add_f32_e32 v205, v204, v205
	v_cvt_pk_bf16_f32 v196, v146, v147
	v_cvt_pk_bf16_f32 v197, v148, v149
	v_cvt_pk_bf16_f32 v198, v150, v151
	v_cvt_pk_bf16_f32 v199, v152, v153
	s_nop 1
	v_permlane32_swap_b32_e32 v196, v198
	v_permlane32_swap_b32_e32 v197, v199
	ds_read_b64_tr_b16 v[146:147], v195 offset:0
	ds_read_b64_tr_b16 v[148:149], v195 offset:2048
	ds_read_b64_tr_b16 v[150:151], v195 offset:512
	ds_read_b64_tr_b16 v[152:153], v195 offset:2560
	ds_read_b64_tr_b16 v[154:155], v195 offset:1024
	ds_read_b64_tr_b16 v[156:157], v195 offset:3072
	ds_read_b64_tr_b16 v[158:159], v195 offset:1536
	ds_read_b64_tr_b16 v[160:161], v195 offset:3584
	s_waitcnt lgkmcnt(6)
	v_mfma_f32_32x32x16_bf16 v[114:129], v[196:199], v[146:149], v[114:129]
	v_exp_f32_e32 v206, v206
	v_exp_f32_e32 v207, v207
	ds_read_b64_tr_b16 v[146:147], v195 offset:16384
	ds_read_b64_tr_b16 v[148:149], v195 offset:18432
	s_waitcnt lgkmcnt(6)
	v_mfma_f32_32x32x16_bf16 v[98:113], v[196:199], v[150:153], v[98:113]
	v_exp_f32_e32 v208, v208
	v_exp_f32_e32 v209, v209
	v_add_f32_e32 v205, v206, v205
	v_add_f32_e32 v205, v207, v205
	ds_read_b64_tr_b16 v[150:151], v195 offset:16896
	ds_read_b64_tr_b16 v[152:153], v195 offset:18944
	s_waitcnt lgkmcnt(6)
	v_mfma_f32_32x32x16_bf16 v[82:97], v[196:199], v[154:157], v[82:97]
	v_exp_f32_e32 v249, v249
	v_exp_f32_e32 v250, v250
	v_add_f32_e32 v205, v208, v205
	v_add_f32_e32 v205, v209, v205
	ds_read_b64_tr_b16 v[154:155], v195 offset:17408
	ds_read_b64_tr_b16 v[156:157], v195 offset:19456
	s_waitcnt lgkmcnt(6)
	v_mfma_f32_32x32x16_bf16 v[66:81], v[196:199], v[158:161], v[66:81]
	v_exp_f32_e32 v251, v251
	v_exp_f32_e32 v248, v248
	v_add_f32_e32 v205, v249, v205
	v_add_f32_e32 v205, v250, v205
	v_cvt_pk_bf16_f32 v200, v206, v207
	ds_read_b64_tr_b16 v[158:159], v195 offset:17920
	ds_read_b64_tr_b16 v[160:161], v195 offset:19968
	s_waitcnt lgkmcnt(6)
	v_mfma_f32_32x32x16_bf16 v[50:65], v[196:199], v[146:149], v[50:65]
	v_add_f32_e32 v205, v251, v205
	v_add_f32_e32 v205, v248, v205
	v_cvt_pk_bf16_f32 v201, v208, v209
	v_cvt_pk_bf16_f32 v202, v249, v250
	ds_read_b64_tr_b16 v[146:147], v195 offset:4096
	ds_read_b64_tr_b16 v[148:149], v195 offset:6144
	s_waitcnt lgkmcnt(6)
	v_mfma_f32_32x32x16_bf16 v[34:49], v[196:199], v[150:153], v[34:49]
	v_cvt_pk_bf16_f32 v203, v251, v248
	ds_read_b64_tr_b16 v[150:151], v195 offset:4608
	ds_read_b64_tr_b16 v[152:153], v195 offset:6656
	s_waitcnt lgkmcnt(6)
	v_mfma_f32_32x32x16_bf16 v[18:33], v[196:199], v[154:157], v[18:33]
	v_permlane32_swap_b32_e32 v200, v202
	v_permlane32_swap_b32_e32 v201, v203
	ds_read_b64_tr_b16 v[154:155], v195 offset:5120
	ds_read_b64_tr_b16 v[156:157], v195 offset:7168
	s_waitcnt lgkmcnt(6)
	v_mfma_f32_32x32x16_bf16 v[2:17], v[196:199], v[158:161], v[2:17]
	ds_read_b64_tr_b16 v[158:159], v195 offset:5632
	ds_read_b64_tr_b16 v[160:161], v195 offset:7680
	s_waitcnt lgkmcnt(6)
	v_mfma_f32_32x32x16_bf16 v[114:129], v[200:203], v[146:149], v[114:129]
	v_fmamk_f32 v130, v130, 0x3e0293ee, v194
	v_fmamk_f32 v131, v131, 0x3e0293ee, v194
	v_fmamk_f32 v132, v132, 0x3e0293ee, v194
	v_fmamk_f32 v133, v133, 0x3e0293ee, v194
	ds_read_b64_tr_b16 v[146:147], v195 offset:20480
	ds_read_b64_tr_b16 v[148:149], v195 offset:22528
	s_waitcnt lgkmcnt(6)
	v_mfma_f32_32x32x16_bf16 v[98:113], v[200:203], v[150:153], v[98:113]
	v_fmamk_f32 v134, v134, 0x3e0293ee, v194
	v_fmamk_f32 v135, v135, 0x3e0293ee, v194
	v_fmamk_f32 v136, v136, 0x3e0293ee, v194
	v_fmamk_f32 v137, v137, 0x3e0293ee, v194
	v_exp_f32_e32 v130, v130
	ds_read_b64_tr_b16 v[150:151], v195 offset:20992
	ds_read_b64_tr_b16 v[152:153], v195 offset:23040
	s_waitcnt lgkmcnt(6)
	v_mfma_f32_32x32x16_bf16 v[82:97], v[200:203], v[154:157], v[82:97]
	v_exp_f32_e32 v131, v131
	v_exp_f32_e32 v132, v132
	ds_read_b64_tr_b16 v[154:155], v195 offset:21504
	ds_read_b64_tr_b16 v[156:157], v195 offset:23552
	s_waitcnt lgkmcnt(6)
	v_mfma_f32_32x32x16_bf16 v[66:81], v[200:203], v[158:161], v[66:81]
	v_exp_f32_e32 v133, v133
	v_exp_f32_e32 v134, v134
	v_add_f32_e32 v204, v130, v131
	ds_read_b64_tr_b16 v[158:159], v195 offset:22016
	ds_read_b64_tr_b16 v[160:161], v195 offset:24064
	s_waitcnt lgkmcnt(6)
; #define SBAR() __builtin_amdgcn_sched_barrier(0)
; __device__ __forceinline__ void finishSM(f32x16& p0, f32x16& p1, float alpha, float& l_reg, bf16x8& pa0, bf16x8& pa1, bf16x8& pa2, bf16x8& pa3) {
; #pragma unroll
;   for (int r = 0; r < 16; ++r) p1[r] = __builtin_amdgcn_exp2f(p1[r]);
;   float ps = 0;
; #pragma unroll
;   for (int r = 0; r < 16; ++r) ps += p0[r];
; #pragma unroll
;   for (int r = 0; r < 16; ++r) ps += p1[r];
;   { auto rr = __builtin_amdgcn_permlane32_swap(__float_as_uint(ps), __float_as_uint(ps), false, false);
;     ps = __uint_as_float(rr[0]) + __uint_as_float(rr[1]); }
;   l_reg = l_reg * alpha + ps;
;     ...
;   PK4(p0, 0, pa0); PK4(p0, 8, pa1); PK4(p1, 0, pa2); PK4(p1, 8, pa3);
;     ...
; }
; template <int D0> __device__ __forceinline__ void pv_one8(f32x16& od, int vb, bf16x8 pa0, bf16x8 pa1, bf16x8 pa2, bf16x8 pa3) {
;   constexpr int HB = (D0 >> 2) * 16384, DD = D0 & 3;
;   const s16x4 l0 = tr_read<HB + v_rd_off(DD, 0, 0)>(vb), h0 = tr_read<HB + v_rd_off(DD, 0, 1)>(vb), l1 = tr_read<HB + v_rd_off(DD, 1, 0)>(vb), h1 = tr_read<HB + v_rd_off(DD, 1, 1)>(vb);
;   const s16x4 l2 = tr_read<HB + v_rd_off(DD, 2, 0)>(vb), h2 = tr_read<HB + v_rd_off(DD, 2, 1)>(vb), l3 = tr_read<HB + v_rd_off(DD, 3, 0)>(vb), h3 = tr_read<HB + v_rd_off(DD, 3, 1)>(vb);
;   asm volatile("s_waitcnt lgkmcnt(0)" ::: "memory"); SBAR();
;     ...
;   od = __builtin_amdgcn_mfma_f32_32x32x16_bf16(pa0, PK(l0, h0), od, 0, 0, 0);
;   od = __builtin_amdgcn_mfma_f32_32x32x16_bf16(pa1, PK(l1, h1), od, 0, 0, 0);
;   od = __builtin_amdgcn_mfma_f32_32x32x16_bf16(pa2, PK(l2, h2), od, 0, 0, 0);
;   od = __builtin_amdgcn_mfma_f32_32x32x16_bf16(pa3, PK(l3, h3), od, 0, 0, 0);
	v_mfma_f32_32x32x16_bf16 v[50:65], v[200:203], v[146:149], v[50:65]
	v_exp_f32_e32 v135, v135
	v_exp_f32_e32 v136, v136
	v_add_f32_e32 v204, v132, v204
	v_add_f32_e32 v204, v133, v204
	ds_read_b64_tr_b16 v[146:147], v195 offset:8192
	ds_read_b64_tr_b16 v[148:149], v195 offset:10240
	s_waitcnt lgkmcnt(6)
	v_mfma_f32_32x32x16_bf16 v[34:49], v[200:203], v[150:153], v[34:49]
	v_exp_f32_e32 v137, v137
	v_add_f32_e32 v204, v134, v204
	v_add_f32_e32 v204, v135, v204
	v_cvt_pk_bf16_f32 v130, v130, v131
	v_cvt_pk_bf16_f32 v131, v132, v133
	ds_read_b64_tr_b16 v[150:151], v195 offset:8704
	ds_read_b64_tr_b16 v[152:153], v195 offset:10752
	s_waitcnt lgkmcnt(6)
	v_mfma_f32_32x32x16_bf16 v[18:33], v[200:203], v[154:157], v[18:33]
	v_add_f32_e32 v204, v136, v204
	v_add_f32_e32 v204, v137, v204
	v_cvt_pk_bf16_f32 v132, v134, v135
	v_cvt_pk_bf16_f32 v133, v136, v137
	ds_read_b64_tr_b16 v[154:155], v195 offset:9216
	ds_read_b64_tr_b16 v[156:157], v195 offset:11264
	s_waitcnt lgkmcnt(6)
	v_mfma_f32_32x32x16_bf16 v[2:17], v[200:203], v[158:161], v[2:17]
	s_nop 0
	v_permlane32_swap_b32_e32 v130, v132
	v_permlane32_swap_b32_e32 v131, v133
	ds_read_b64_tr_b16 v[158:159], v195 offset:9728
	ds_read_b64_tr_b16 v[160:161], v195 offset:11776
	s_waitcnt lgkmcnt(6)
	v_mfma_f32_32x32x16_bf16 v[114:129], v[130:133], v[146:149], v[114:129]
	v_fmamk_f32 v138, v138, 0x3e0293ee, v194
	v_fmamk_f32 v139, v139, 0x3e0293ee, v194
	v_fmamk_f32 v140, v140, 0x3e0293ee, v194
	v_fmamk_f32 v141, v141, 0x3e0293ee, v194
	ds_read_b64_tr_b16 v[146:147], v195 offset:24576
	ds_read_b64_tr_b16 v[148:149], v195 offset:26624
	s_waitcnt lgkmcnt(6)
	v_mfma_f32_32x32x16_bf16 v[98:113], v[130:133], v[150:153], v[98:113]
	v_fmamk_f32 v142, v142, 0x3e0293ee, v194
	v_fmamk_f32 v143, v143, 0x3e0293ee, v194
	v_fmamk_f32 v144, v144, 0x3e0293ee, v194
	v_fmamk_f32 v145, v145, 0x3e0293ee, v194
	v_exp_f32_e32 v138, v138
	ds_read_b64_tr_b16 v[150:151], v195 offset:25088
	ds_read_b64_tr_b16 v[152:153], v195 offset:27136
	s_waitcnt lgkmcnt(6)
	v_mfma_f32_32x32x16_bf16 v[82:97], v[130:133], v[154:157], v[82:97]
	v_exp_f32_e32 v139, v139
	v_exp_f32_e32 v140, v140
	ds_read_b64_tr_b16 v[154:155], v195 offset:25600
	ds_read_b64_tr_b16 v[156:157], v195 offset:27648
	s_waitcnt lgkmcnt(6)
	v_mfma_f32_32x32x16_bf16 v[66:81], v[130:133], v[158:161], v[66:81]
	v_exp_f32_e32 v141, v141
	v_exp_f32_e32 v142, v142
	v_add_f32_e32 v204, v138, v204
	v_add_f32_e32 v204, v139, v204
	ds_read_b64_tr_b16 v[158:159], v195 offset:26112
	ds_read_b64_tr_b16 v[160:161], v195 offset:28160
	s_waitcnt lgkmcnt(6)
	v_mfma_f32_32x32x16_bf16 v[50:65], v[130:133], v[146:149], v[50:65]
	v_exp_f32_e32 v143, v143
	v_exp_f32_e32 v144, v144
	v_add_f32_e32 v204, v140, v204
	v_add_f32_e32 v204, v141, v204
	ds_read_b64_tr_b16 v[146:147], v195 offset:12288
	ds_read_b64_tr_b16 v[148:149], v195 offset:14336
	s_waitcnt lgkmcnt(6)
	v_mfma_f32_32x32x16_bf16 v[34:49], v[130:133], v[150:153], v[34:49]
	v_exp_f32_e32 v145, v145
	v_add_f32_e32 v204, v142, v204
	v_add_f32_e32 v204, v143, v204
	v_cvt_pk_bf16_f32 v134, v138, v139
	v_cvt_pk_bf16_f32 v135, v140, v141
	ds_read_b64_tr_b16 v[150:151], v195 offset:12800
	ds_read_b64_tr_b16 v[152:153], v195 offset:14848
	s_waitcnt lgkmcnt(6)
	v_mfma_f32_32x32x16_bf16 v[18:33], v[130:133], v[154:157], v[18:33]
	v_add_f32_e32 v204, v144, v204
	v_add_f32_e32 v204, v145, v204
	v_cvt_pk_bf16_f32 v136, v142, v143
	v_cvt_pk_bf16_f32 v137, v144, v145
	ds_read_b64_tr_b16 v[154:155], v195 offset:13312
	ds_read_b64_tr_b16 v[156:157], v195 offset:15360
	s_waitcnt lgkmcnt(6)
	v_mfma_f32_32x32x16_bf16 v[2:17], v[130:133], v[158:161], v[2:17]
	s_nop 0
	v_permlane32_swap_b32_e32 v134, v136
	v_permlane32_swap_b32_e32 v135, v137
	ds_read_b64_tr_b16 v[158:159], v195 offset:13824
	ds_read_b64_tr_b16 v[160:161], v195 offset:15872
	s_waitcnt lgkmcnt(6)
	v_mfma_f32_32x32x16_bf16 v[114:129], v[134:137], v[146:149], v[114:129]
	v_add_f32_e32 v204, v205, v204
	ds_read_b64_tr_b16 v[146:147], v195 offset:28672
	ds_read_b64_tr_b16 v[148:149], v195 offset:30720
	s_waitcnt lgkmcnt(6)
	v_mfma_f32_32x32x16_bf16 v[98:113], v[134:137], v[150:153], v[98:113]
	v_mov_b32_e32 v206, v204
	ds_read_b64_tr_b16 v[150:151], v195 offset:29184
	ds_read_b64_tr_b16 v[152:153], v195 offset:31232
	s_waitcnt lgkmcnt(6)
	v_mfma_f32_32x32x16_bf16 v[82:97], v[134:137], v[154:157], v[82:97]
	ds_read_b64_tr_b16 v[154:155], v195 offset:29696
	ds_read_b64_tr_b16 v[156:157], v195 offset:31744
	s_waitcnt lgkmcnt(6)
	v_mfma_f32_32x32x16_bf16 v[66:81], v[134:137], v[158:161], v[66:81]
	v_permlane32_swap_b32_e32 v204, v206
	ds_read_b64_tr_b16 v[158:159], v195 offset:30208
	ds_read_b64_tr_b16 v[160:161], v195 offset:32256
	s_waitcnt lgkmcnt(6)
	v_mfma_f32_32x32x16_bf16 v[50:65], v[134:137], v[146:149], v[50:65]
	v_add_f32_e32 v248, v204, v206
	v_fmac_f32_e32 v248, v247, v0
	s_waitcnt lgkmcnt(4)
	v_mfma_f32_32x32x16_bf16 v[34:49], v[134:137], v[150:153], v[34:49]
	v_mov_b32_e32 v247, v248
	s_waitcnt lgkmcnt(2)
	v_mfma_f32_32x32x16_bf16 v[18:33], v[134:137], v[154:157], v[18:33]
	s_waitcnt lgkmcnt(0)
	v_mfma_f32_32x32x16_bf16 v[2:17], v[134:137], v[158:161], v[2:17]
